# combined: phase-0a rebalancing + DPP wave sums + next-tile DMA prefetch (gemm_in, FF1) + glu/ssm_out epilogue load batching + attention prologue K(0)-only wait
# speedup vs baseline: 1.0074x; 1.0025x over previous
; DI int bidx() { int b = blockIdx.x; asm volatile("" : "+s"(b)); return b; }
; DI void phase0a(const Params& p, char* lds) {
;     ...
;   for (int it = bidx(); it < NITEMS; it += gridDim.x) {
;     if (it < N_SSM) { ssm_tables(p, it >> 1, it & 1, lds); continue; }
; __global__ void __launch_bounds__(NT) fwd_megakernel(Params p) {
;   __shared__ __attribute__((aligned(16))) char lds[LDS_BYTES];
;   cg::grid_group grid = cg::this_grid();
;   phase0a(p, lds);
_Z14fwd_megakernel6Params:
	s_add_u32 s4, s0, 0x130
	s_addc_u32 s5, s1, 0
	v_and_b32_e32 v162, 0x3ff, v0
	v_writelane_b32 v254, s4, 0
	v_mov_b32_e32 v1, v162
	s_mov_b32 s74, s2
	v_writelane_b32 v254, s5, 1
	v_writelane_b32 v254, s0, 2
	s_load_dword s12, s[0:1], 0x130
	s_cmpk_gt_i32 s74, 0x11a0
	v_writelane_b32 v254, s1, 3
	v_writelane_b32 v254, s2, 4
	s_waitcnt lgkmcnt(0)
	s_mov_b32 s20, 0
	v_writelane_b32 v255, s20, 52
	s_mov_b32 s20, 0
	v_writelane_b32 v255, s20, 51
	v_writelane_b32 v254, s12, 5
	s_cbranch_scc1 .LBB0_91
	s_movk_i32 s0, 0x1000
	v_and_b32_e32 v58, 7, v1
	v_cmp_gt_i32_e64 s[4:5], s0, v1
	v_cvt_f64_u32_e32 v[2:3], v58
	s_mov_b32 s0, 0x471b3a95
	v_ldexp_f64 v[2:3], -v[2:3], -3
	s_mov_b32 s1, 0x4032ee7b
	v_mul_f64 v[20:21], v[2:3], s[0:1]
	v_rndne_f64_e32 v[22:23], v[20:21]
	v_add_f64 v[2:3], v[20:21], -v[22:23]
	s_mov_b32 s45, 0x3c7abc9e
	s_mov_b32 s44, 0x3b39803f
	v_mul_f64 v[24:25], v[2:3], s[44:45]
	s_mov_b32 s47, 0x3fe62e42
	s_mov_b32 s46, 0xfefa39ef
	v_fmac_f64_e32 v[24:25], s[46:47], v[2:3]
	v_mov_b32_e32 v2, 0xfca7ab0c
	v_mov_b32_e32 v3, 0x3e928af3
	s_mov_b32 s48, 0x6a5dcb37
	s_mov_b32 s49, 0x3e5ade15
	v_mov_b64_e32 v[6:7], v[2:3]
	v_mov_b32_e32 v4, 0x623fde64
	v_mov_b32_e32 v5, 0x3ec71dee
	v_fmac_f64_e32 v[6:7], s[48:49], v[24:25]
	v_mov_b64_e32 v[8:9], v[4:5]
	v_fmac_f64_e32 v[8:9], v[24:25], v[6:7]
	v_mov_b32_e32 v6, 0x7c89e6b0
	v_mov_b32_e32 v7, 0x3efa0199
	v_mov_b64_e32 v[10:11], v[6:7]
	v_fmac_f64_e32 v[10:11], v[24:25], v[8:9]
	v_mov_b32_e32 v8, 0x14761f6e
	v_mov_b32_e32 v9, 0x3f2a01a0
	v_mov_b64_e32 v[12:13], v[8:9]
	v_fmac_f64_e32 v[12:13], v[24:25], v[10:11]
	v_mov_b32_e32 v10, 0x1852b7b0
	v_mov_b32_e32 v11, 0x3f56c16c
	v_mov_b64_e32 v[14:15], v[10:11]
	v_fmac_f64_e32 v[14:15], v[24:25], v[12:13]
	v_mov_b32_e32 v12, 0x11122322
	v_mov_b32_e32 v13, 0x3f811111
	v_mov_b64_e32 v[16:17], v[12:13]
	v_fmac_f64_e32 v[16:17], v[24:25], v[14:15]
	v_mov_b32_e32 v14, 0x555502a1
	v_mov_b32_e32 v15, 0x3fa55555
	v_mov_b64_e32 v[18:19], v[14:15]
	v_fmac_f64_e32 v[18:19], v[24:25], v[16:17]
	v_mov_b32_e32 v16, 0x55555511
	v_mov_b32_e32 v17, 0x3fc55555
	v_mov_b64_e32 v[26:27], v[16:17]
	v_fmac_f64_e32 v[26:27], v[24:25], v[18:19]
	v_mov_b32_e32 v18, 11
	v_mov_b32_e32 v19, 0x3fe00000
	v_readlane_b32 s2, v254, 2
	v_mov_b64_e32 v[28:29], v[18:19]
	v_readlane_b32 s3, v254, 3
	v_fmac_f64_e32 v[28:29], v[24:25], v[26:27]
	s_load_dwordx2 s[54:55], s[2:3], 0x128
	s_load_dwordx2 s[0:1], s[2:3], 0x118
	v_fma_f64 v[26:27], v[24:25], v[28:29], 1.0
	s_mov_b32 s50, 0
	s_mov_b32 s52, 0
	v_fma_f64 v[24:25], v[24:25], v[26:27], 1.0
	v_cvt_i32_f64_e32 v22, v[22:23]
	s_mov_b32 s51, 0x40900000
	s_mov_b32 s53, 0xc090cc00
	v_ldexp_f64 v[22:23], v[24:25], v22
	v_mov_b32_e32 v59, 0x7ff00000
	v_cmp_nlt_f64_e32 vcc, s[50:51], v[20:21]
	v_cmp_ngt_f64_e64 s[8:9], s[52:53], v[20:21]
	s_waitcnt lgkmcnt(0)
	v_writelane_b32 v254, s0, 6
	v_cndmask_b32_e32 v23, v59, v23, vcc
	s_and_b64 vcc, s[8:9], vcc
	s_add_u32 s33, s54, 0x1880000
	v_writelane_b32 v254, s1, 7
	s_addc_u32 s0, s55, 0
	v_writelane_b32 v254, s0, 8
	s_add_u32 s0, s54, 0x1080000
	v_writelane_b32 v254, s0, 9
	s_addc_u32 s0, s55, 0
	v_writelane_b32 v254, s0, 10
	s_add_u32 s0, s54, 0xe80000
	v_writelane_b32 v254, s0, 11
	s_addc_u32 s0, s55, 0
	v_writelane_b32 v254, s0, 12
	s_load_dwordx2 s[0:1], s[2:3], 0xe8
	s_load_dwordx2 s[92:93], s[2:3], 0x70
	s_load_dwordx4 s[28:31], s[2:3], 0xd0
	s_load_dwordx8 s[20:27], s[2:3], 0xf8
	s_mov_b32 s66, 0x6dc9c883
	s_mov_b32 s68, 0x652b82fe
	s_mov_b32 s6, 0x54442d18
	s_waitcnt lgkmcnt(0)
	v_writelane_b32 v254, s0, 14
	s_mov_b32 s60, 0x33145c00
	s_mov_b32 s88, 0x46cc5e42
	v_writelane_b32 v254, s1, 15
	s_add_u32 s0, s54, 0xe00000
	v_writelane_b32 v254, s0, 16
	s_addc_u32 s0, s55, 0
	v_writelane_b32 v254, s0, 18
	s_add_u32 s0, s54, 0xd00000
	v_writelane_b32 v254, s0, 19
	s_addc_u32 s0, s55, 0
	v_writelane_b32 v254, s0, 20
	s_add_u32 s0, s54, 0xb00000
	v_writelane_b32 v254, s0, 22
	s_addc_u32 s0, s55, 0
	v_writelane_b32 v254, s0, 24
	v_writelane_b32 v254, s20, 26
	s_add_u32 s86, s54, 0x43a4000
	s_addc_u32 s87, s55, 0
	v_writelane_b32 v254, s21, 27
	v_writelane_b32 v254, s22, 28
	v_writelane_b32 v254, s23, 29
	s_add_u32 s62, s54, 0x42a4000
	v_writelane_b32 v254, s24, 30
	s_addc_u32 s63, s55, 0
	v_writelane_b32 v254, s25, 31
	s_add_u32 s64, s54, 0x4280000
	v_writelane_b32 v254, s26, 32
	s_addc_u32 s65, s55, 0
	v_writelane_b32 v254, s27, 33
	s_load_dwordx8 s[20:27], s[2:3], 0x50
	s_load_dwordx8 s[36:43], s[2:3], 0x10
	s_add_u32 s12, s54, 0x4080000
	s_addc_u32 s13, s55, 0
	s_add_u32 s14, s54, 0x2080000
	s_mul_i32 s0, s74, 24
	s_mov_b32 s90, 0x55555555
	s_mov_b32 s80, 0xf9a43bb8
	s_mov_b32 s35, 0
	v_cmp_eq_u32_e64 s[84:85], 0, v1
	v_cndmask_b32_e64 v21, 0, v23, s[8:9]
	v_cndmask_b32_e32 v20, 0, v22, vcc
	s_addc_u32 s15, s55, 0
	s_add_i32 s34, s0, 0xfffffa00
	v_mov_b32_e32 v23, 0
	s_movk_i32 s17, 0x5800
	s_mov_b32 s67, 0x3fc45f30
	s_movk_i32 s59, 0x1800
	s_movk_i32 s18, 0x400
	s_movk_i32 s19, 0x6000
	s_mov_b32 s69, 0x3ff71547
	s_mov_b32 s47, 0xbfe62e42
	s_mov_b32 s45, 0xbc7abc9e
	s_mov_b32 s7, 0xbff921fb
	s_mov_b32 s61, 0xbc91a626
	s_mov_b32 s89, 0xbda907db
	s_mov_b32 s91, 0xbfc55555
	s_mov_b32 s81, 0x3de5e0b2
	s_brev_b32 s58, 1
	s_movk_i32 s16, 0x7dff
	v_mov_b32_e32 v60, 0x7f800000
	v_mov_b32_e32 v61, 0x40100000
	v_mov_b32_e32 v62, 0x3ff00000
	v_mov_b32_e32 v24, 0x9037ab78
	v_mov_b32_e32 v25, 0x3e21eeb6
	v_mov_b32_e32 v26, 0xa17f65f6
	v_mov_b32_e32 v27, 0xbe927e4f
	v_mov_b32_e32 v28, 0x19f4ec90
	v_mov_b32_e32 v29, 0x3efa01a0
	v_mov_b32_e32 v30, 0x16c16967
	v_mov_b32_e32 v31, 0xbf56c16c
	v_mov_b32_e32 v32, 0x55555555
	v_mov_b32_e32 v34, 0xb42fdfa7
	v_mov_b32_e32 v35, 0xbe5ae600
	v_mov_b32_e32 v36, 0x796cde01
	v_mov_b32_e32 v37, 0x3ec71de3
	v_mov_b32_e32 v38, 0x19e83e5c
	v_mov_b32_e32 v39, 0xbf2a01a0
	v_mov_b32_e32 v40, 0x11110bb3
	v_mov_b32_e32 v63, 0x7ff80000
	v_mov_b32_e32 v64, 0x4200
	s_mov_b64 s[82:83], 0x180000
	s_mov_b32 s71, 0x3ff921fb
	s_mov_b32 s73, 0x3c91a626
	s_mov_b32 s78, 0x33145c07
	s_mov_b32 s77, 0x3fe45f30
	s_branch .LBB0_4
